# split-K tail of FFN down-proj phases (P7,P14) 16-way over all 256 WGs instead of 8-way over 128
# baseline (speedup 1.0000x reference)
.LBB0_694:
	s_add_u32 s56, s70, 0x11000
	v_and_b32_e32 v3, 15, v143
	v_lshlrev_b32_e32 v17, 1, v14
	v_lshlrev_b32_e32 v18, 2, v143
	s_addc_u32 s57, s71, 0
	v_lshl_or_b32 v1, s0, 6, v3
	v_lshl_or_b32 v3, v3, 6, v17
	s_lshl_b32 s0, s0, 13
	v_and_b32_e32 v18, 32, v18
	v_bitop3_b32 v19, v3, s0, v18 bitop3:0xde
	s_lshl_b32 s0, s1, 5
	s_mov_b64 s[12:13], 0x80
	s_sext_i32_i8 s46, s5
	s_and_b32 s5, s0, 0x60
	v_lshlrev_b32_e32 v3, 6, v143
	s_movk_i32 s0, 0x3c0
	s_add_i32 m0, s42, 0x18000
	v_lshl_add_u64 v[10:11], v[10:11], 0, s[12:13]
	v_and_or_b32 v3, v3, s0, v17
	s_lshl_b32 s0, s5, 7
	s_waitcnt vmcnt(2)
	s_barrier
	global_load_lds_dwordx4 v[10:11], off
	v_lshl_add_u64 v[8:9], v[8:9], 0, s[12:13]
	s_add_i32 m0, s42, 0x1a000
	s_add_i32 s58, s42, 0x8000
	s_add_i32 s59, s42, 0xa000
	v_bitop3_b32 v150, s0, v3, v18 bitop3:0xf6
	global_load_lds_dwordx4 v[8:9], off
	v_lshl_add_u64 v[6:7], v[6:7], 0, s[12:13]
	s_mov_b32 m0, s58
	s_add_u32 s0, s34, 0x160080
	global_load_lds_dwordx4 v[6:7], off
	v_lshl_add_u64 v[4:5], v[4:5], 0, s[12:13]
	s_mov_b32 m0, s59
	s_addc_u32 s1, s35, 0
	global_load_lds_dwordx4 v[4:5], off
	s_add_i32 m0, s42, 0x1c000
	v_lshl_add_u64 v[4:5], s[0:1], 0, v[132:133]
	global_load_lds_dwordx4 v[4:5], off
	v_lshl_add_u64 v[4:5], s[0:1], 0, v[136:137]
	s_add_i32 m0, s42, 0x1e000
	s_cmpk_lt_u32 s4, 0x100
	global_load_lds_dwordx4 v[4:5], off
	s_cselect_b64 s[20:21], -1, 0
	s_cmpk_lt_i32 s2, 0x100
	s_cselect_b64 s[22:23], -1, 0
	s_and_b32 s61, s2, 15
	s_ashr_i32 s4, s2, 7
	v_readlane_b32 s18, v242, 53
	s_ashr_i32 s60, s2, 4
	s_add_i32 s62, s4, 32
	s_mul_i32 s4, s61, 4
	v_mov_b32_e32 v3, v133
	v_readlane_b32 s19, v242, 54
	s_and_b32 s63, s60, 7
	s_add_i32 s4, s4, 24
	s_waitcnt vmcnt(6)
	v_lshl_add_u64 v[138:139], s[18:19], 0, v[2:3]
	s_cmp_lt_u32 s61, 12
	s_mul_i32 s24, s61, 6
	v_add_u16_e32 v2, v12, v13
	s_cselect_b32 s66, 6, 4
	s_cselect_b32 s24, s24, s4
	v_lshrrev_b16_e32 v2, 1, v2
	s_add_i32 s67, 0, 0x10000
	s_add_i32 s76, 0, 0x14000
	v_cmp_eq_u32_e64 s[0:1], 0, v143
	v_or_b32_e32 v151, s5, v14
	v_add_lshl_u32 v140, v15, v2, 1
	v_mov_b32_e32 v141, v133
	v_add_lshl_u32 v144, v16, v2, 1
	v_mov_b32_e32 v145, v133
	s_mov_b64 s[4:5], -1
	s_movk_i32 s47, 0x58
	s_mov_b32 s77, -1
	v_add_u32_e32 v152, s67, v150
	v_add_u32_e32 v153, s76, v150
	v_add_u32_e32 v154, 0, v19
	s_mov_b32 s52, 0
	s_barrier
	s_branch .LBB0_697

.LBB0_705:
	v_lshl_add_u32 v148, s8, 8, v1
	v_lshl_or_b32 v146, s46, 8, v151
	s_mov_b64 s[30:31], -1
	s_cmp_gt_i32 s77, -1
	v_cvt_pk_bf16_f32 v66, v66, v67
	v_cvt_pk_bf16_f32 v67, v68, v69
	v_cvt_pk_bf16_f32 v68, v126, v127
	v_cvt_pk_bf16_f32 v69, v128, v129
	v_cvt_pk_bf16_f32 v62, v62, v63
	v_cvt_pk_bf16_f32 v63, v64, v65
	v_cvt_pk_bf16_f32 v64, v58, v59
	v_cvt_pk_bf16_f32 v65, v60, v61
	v_cvt_pk_bf16_f32 v58, v122, v123
	v_cvt_pk_bf16_f32 v59, v124, v125
	v_cvt_pk_bf16_f32 v60, v118, v119
	v_cvt_pk_bf16_f32 v61, v120, v121
	v_cvt_pk_bf16_f32 v54, v54, v55
	v_cvt_pk_bf16_f32 v55, v56, v57
	v_cvt_pk_bf16_f32 v56, v50, v51
	v_cvt_pk_bf16_f32 v57, v52, v53
	v_cvt_pk_bf16_f32 v50, v114, v115
	v_cvt_pk_bf16_f32 v51, v116, v117
	v_cvt_pk_bf16_f32 v52, v110, v111
	v_cvt_pk_bf16_f32 v53, v112, v113
	v_cvt_pk_bf16_f32 v46, v46, v47
	v_cvt_pk_bf16_f32 v47, v48, v49
	v_cvt_pk_bf16_f32 v48, v42, v43
	v_cvt_pk_bf16_f32 v49, v44, v45
	v_cvt_pk_bf16_f32 v42, v106, v107
	v_cvt_pk_bf16_f32 v43, v108, v109
	v_cvt_pk_bf16_f32 v44, v102, v103
	v_cvt_pk_bf16_f32 v45, v104, v105
	v_cvt_pk_bf16_f32 v38, v38, v39
	v_cvt_pk_bf16_f32 v39, v40, v41
	v_cvt_pk_bf16_f32 v40, v98, v99
	v_cvt_pk_bf16_f32 v41, v100, v101
	v_cvt_pk_bf16_f32 v34, v34, v35
	v_cvt_pk_bf16_f32 v35, v36, v37
	v_cvt_pk_bf16_f32 v36, v94, v95
	v_cvt_pk_bf16_f32 v37, v96, v97
	v_cvt_pk_bf16_f32 v30, v30, v31
	v_cvt_pk_bf16_f32 v31, v32, v33
	v_cvt_pk_bf16_f32 v32, v26, v27
	v_cvt_pk_bf16_f32 v33, v28, v29
	v_cvt_pk_bf16_f32 v26, v90, v91
	v_cvt_pk_bf16_f32 v27, v92, v93
	v_cvt_pk_bf16_f32 v28, v86, v87
	v_cvt_pk_bf16_f32 v29, v88, v89
	v_cvt_pk_bf16_f32 v22, v22, v23
	v_cvt_pk_bf16_f32 v23, v24, v25
	v_cvt_pk_bf16_f32 v24, v18, v19
	v_cvt_pk_bf16_f32 v25, v20, v21
	v_cvt_pk_bf16_f32 v18, v82, v83
	v_cvt_pk_bf16_f32 v19, v84, v85
	v_cvt_pk_bf16_f32 v20, v78, v79
	v_cvt_pk_bf16_f32 v21, v80, v81
	v_cvt_pk_bf16_f32 v14, v14, v15
	v_cvt_pk_bf16_f32 v15, v16, v17
	v_cvt_pk_bf16_f32 v16, v10, v11
	v_cvt_pk_bf16_f32 v17, v12, v13
	v_cvt_pk_bf16_f32 v10, v74, v75
	v_cvt_pk_bf16_f32 v11, v76, v77
	v_cvt_pk_bf16_f32 v12, v70, v71
	v_cvt_pk_bf16_f32 v13, v72, v73
	s_cbranch_scc0 .LBB0_719
	s_lshl_b32 s30, s52, 4
	s_add_i32 s34, s30, s77
	s_ashr_i32 s35, s34, 31
	s_lshl_b64 s[34:35], s[34:35], 17
	v_lshl_add_u64 v[74:75], v[138:139], 0, s[34:35]
	s_movk_i32 s8, 0x2000
	v_add_co_u32_e32 v70, vcc, s8, v74
	s_movk_i32 s8, 0x4000
	s_nop 0
	v_addc_co_u32_e32 v71, vcc, 0, v75, vcc
	global_store_dwordx4 v[70:71], v[62:65], off
	v_add_co_u32_e32 v70, vcc, s8, v74
	s_movk_i32 s8, 0x6000
	s_nop 0
	v_addc_co_u32_e32 v71, vcc, 0, v75, vcc
	global_store_dwordx4 v[70:71], v[58:61], off
	v_add_co_u32_e32 v70, vcc, s8, v74
	s_mov_b32 s8, 0x8000
	s_nop 0
	v_addc_co_u32_e32 v71, vcc, 0, v75, vcc
	global_store_dwordx4 v[70:71], v[54:57], off
	v_add_co_u32_e32 v70, vcc, s8, v74
	s_mov_b32 s8, 0xa000
	s_nop 0
	v_addc_co_u32_e32 v71, vcc, 0, v75, vcc
	global_store_dwordx4 v[70:71], v[50:53], off
	v_add_co_u32_e32 v70, vcc, s8, v74
	s_mov_b32 s8, 0xc000
	s_nop 0
	v_addc_co_u32_e32 v71, vcc, 0, v75, vcc
	global_store_dwordx4 v[70:71], v[46:49], off
	v_add_co_u32_e32 v70, vcc, s8, v74
	s_mov_b32 s8, 0xe000
	s_nop 0
	v_addc_co_u32_e32 v71, vcc, 0, v75, vcc
	global_store_dwordx4 v[70:71], v[42:45], off
	v_add_co_u32_e32 v70, vcc, s8, v74
	s_mov_b32 s8, 0x10000
	s_nop 0
	v_addc_co_u32_e32 v71, vcc, 0, v75, vcc
	global_store_dwordx4 v[70:71], v[38:41], off
	v_add_co_u32_e32 v70, vcc, s8, v74
	s_mov_b32 s8, 0x12000
	s_nop 0
	v_addc_co_u32_e32 v71, vcc, 0, v75, vcc
	global_store_dwordx4 v[70:71], v[34:37], off
	v_add_co_u32_e32 v70, vcc, s8, v74
	s_mov_b32 s8, 0x14000
	s_nop 0
	v_addc_co_u32_e32 v71, vcc, 0, v75, vcc
	global_store_dwordx4 v[70:71], v[30:33], off
	v_add_co_u32_e32 v70, vcc, s8, v74
	s_mov_b32 s8, 0x16000
	s_nop 0
	v_addc_co_u32_e32 v71, vcc, 0, v75, vcc
	global_store_dwordx4 v[70:71], v[26:29], off
	v_add_co_u32_e32 v70, vcc, s8, v74
	s_mov_b32 s8, 0x18000
	s_nop 0
	v_addc_co_u32_e32 v71, vcc, 0, v75, vcc
	global_store_dwordx4 v[70:71], v[22:25], off
	v_add_co_u32_e32 v70, vcc, s8, v74
	s_mov_b32 s8, 0x1a000
	s_nop 0
	v_addc_co_u32_e32 v71, vcc, 0, v75, vcc
	global_store_dwordx4 v[70:71], v[18:21], off
	v_add_co_u32_e32 v70, vcc, s8, v74
	s_mov_b32 s8, 0x1c000
	s_nop 0
	v_addc_co_u32_e32 v71, vcc, 0, v75, vcc
	global_store_dwordx4 v[70:71], v[14:17], off
	v_add_co_u32_e32 v70, vcc, s8, v74
	global_store_dwordx4 v[74:75], v[66:69], off
	s_nop 0
	v_addc_co_u32_e32 v71, vcc, 0, v75, vcc
	v_add_co_u32_e32 v74, vcc, 0x1e000, v74
	global_store_dwordx4 v[70:71], v[10:13], off
	v_cvt_pk_bf16_f32 v70, v6, v7
	v_cvt_pk_bf16_f32 v71, v8, v9
	v_cvt_pk_bf16_f32 v72, v2, v3
	v_cvt_pk_bf16_f32 v73, v4, v5
	v_addc_co_u32_e32 v75, vcc, 0, v75, vcc
	global_store_dwordx4 v[74:75], v[70:73], off
	s_waitcnt vmcnt(0)
	s_waitcnt vmcnt(0)
	s_barrier
	s_and_saveexec_b64 s[34:35], s[0:1]
	s_cbranch_execz .LBB0_718
	s_lshl_b32 s36, s52, 6
	s_mov_b64 s[46:47], exec
	s_ashr_i32 s37, s36, 31
	s_lshl_b64 s[36:37], s[36:37], 2
	buffer_wbl2 sc1
	s_waitcnt vmcnt(0)
	v_mbcnt_lo_u32_b32 v70, s46, 0
	s_add_u32 s36, s56, s36
	v_mbcnt_hi_u32_b32 v70, s47, v70
	s_addc_u32 s37, s57, s37
	v_cmp_eq_u32_e32 vcc, 0, v70
	s_and_saveexec_b64 s[52:53], vcc
	s_cbranch_execz .LBB0_709
	s_bcnt1_i32_b64 s8, s[46:47]
	v_mov_b32_e32 v70, s8
	global_atomic_add v133, v70, s[36:37]

.LBB0_711:
	global_load_dword v70, v133, s[36:37] sc1
	s_mov_b64 s[46:47], -1
	s_waitcnt vmcnt(0)
	v_cmp_lt_u32_e32 vcc, 15, v70
	s_cbranch_vccnz .LBB0_710
	s_sleep 2
	global_load_dword v70, v133, s[36:37] sc1
	s_waitcnt vmcnt(0)
	v_cmp_gt_u32_e32 vcc, 16, v70
	s_cbranch_vccz .LBB0_710
	s_sleep 2
	global_load_dword v70, v133, s[36:37] sc1
	s_waitcnt vmcnt(0)
	v_cmp_gt_u32_e32 vcc, 16, v70
	s_cbranch_vccz .LBB0_710
	s_sleep 2
	global_load_dword v70, v133, s[36:37] sc1
	s_waitcnt vmcnt(0)
	v_cmp_gt_u32_e32 vcc, 16, v70
	s_cbranch_vccz .LBB0_710
	s_sleep 2
	global_load_dword v70, v133, s[36:37] sc1
	s_waitcnt vmcnt(0)
	v_cmp_gt_u32_e32 vcc, 16, v70
	s_cbranch_vccz .LBB0_710
	s_add_i32 s8, s8, -5
	s_cmp_eq_u32 s8, 0
	s_cselect_b64 s[46:47], -1, 0
	s_sleep 2
	s_branch .LBB0_710

.LBB0_718:
	s_or_b64 exec, exec, s[34:35]
	s_ashr_i32 s31, s30, 31
	s_lshl_b64 s[30:31], s[30:31], 17
	v_lshl_add_u64 v[70:71], v[138:139], 0, s[30:31]
	s_lshl_b32 s30, s77, 13
	s_mov_b32 s31, 0
	v_lshl_add_u64 v[70:71], v[70:71], 0, s[30:31]
	s_mov_b64 s[30:31], 0x20000
	s_barrier
	global_load_dwordx4 v[2:5], v[70:71], off
	v_lshl_add_u64 v[72:73], v[70:71], 0, s[30:31]
	global_load_dwordx4 v[6:9], v[72:73], off
	v_lshl_add_u64 v[72:73], v[72:73], 0, s[30:31]
	global_load_dwordx4 v[10:13], v[72:73], off
	v_lshl_add_u64 v[72:73], v[72:73], 0, s[30:31]
	global_load_dwordx4 v[14:17], v[72:73], off
	v_lshl_add_u64 v[72:73], v[72:73], 0, s[30:31]
	global_load_dwordx4 v[18:21], v[72:73], off
	v_lshl_add_u64 v[72:73], v[72:73], 0, s[30:31]
	global_load_dwordx4 v[22:25], v[72:73], off
	v_lshl_add_u64 v[72:73], v[72:73], 0, s[30:31]
	global_load_dwordx4 v[26:29], v[72:73], off
	v_lshl_add_u64 v[72:73], v[72:73], 0, s[30:31]
	global_load_dwordx4 v[30:33], v[72:73], off
	v_lshl_add_u64 v[72:73], v[72:73], 0, s[30:31]
	global_load_dwordx4 v[34:37], v[72:73], off
	v_lshl_add_u64 v[72:73], v[72:73], 0, s[30:31]
	global_load_dwordx4 v[38:41], v[72:73], off
	v_lshl_add_u64 v[72:73], v[72:73], 0, s[30:31]
	global_load_dwordx4 v[42:45], v[72:73], off
	v_lshl_add_u64 v[72:73], v[72:73], 0, s[30:31]
	global_load_dwordx4 v[46:49], v[72:73], off
	v_lshl_add_u64 v[72:73], v[72:73], 0, s[30:31]
	global_load_dwordx4 v[50:53], v[72:73], off
	v_lshl_add_u64 v[72:73], v[72:73], 0, s[30:31]
	global_load_dwordx4 v[54:57], v[72:73], off
	v_lshl_add_u64 v[72:73], v[72:73], 0, s[30:31]
	global_load_dwordx4 v[58:61], v[72:73], off
	v_lshl_add_u64 v[72:73], v[72:73], 0, s[30:31]
	global_load_dwordx4 v[62:65], v[72:73], off
	s_lshl_b32 s8, s77, 4
	s_and_b32 s8, s8, 0x80
	v_add_u32_e32 v160, s8, v148
	s_lshl_b32 s8, s77, 3
	s_and_b32 s8, s8, 48
	v_or_b32_e32 v160, s8, v160
	v_ashrrev_i32_e32 v161, 31, v160
	v_ashrrev_i32_e32 v147, 31, v146
	v_lshlrev_b64 v[102:103], 12, v[160:161]
	s_and_b32 s8, s77, 1
	s_lshl_b32 s8, s8, 8
	s_sub_u32 s30, s8, 0x100
	s_subb_u32 s31, 0, 0
	v_lshl_add_u64 v[102:103], v[102:103], 0, s[30:31]
	s_mov_b64 s[30:31], 0
	s_waitcnt vmcnt(15)
	v_lshlrev_b32_e32 v74, 16, v2
	v_and_b32_e32 v75, 0xffff0000, v2
	v_lshlrev_b32_e32 v76, 16, v3
	v_and_b32_e32 v77, 0xffff0000, v3
	v_lshlrev_b32_e32 v104, 16, v4
	v_and_b32_e32 v105, 0xffff0000, v4
	v_lshlrev_b32_e32 v106, 16, v5
	v_and_b32_e32 v107, 0xffff0000, v5
	s_waitcnt vmcnt(14)
	v_lshlrev_b32_e32 v108, 16, v6
	v_and_b32_e32 v109, 0xffff0000, v6
	v_pk_add_f32 v[74:75], v[74:75], v[108:109]
	v_lshlrev_b32_e32 v110, 16, v7
	v_and_b32_e32 v111, 0xffff0000, v7
	v_pk_add_f32 v[76:77], v[76:77], v[110:111]
	v_lshlrev_b32_e32 v112, 16, v8
	v_and_b32_e32 v113, 0xffff0000, v8
	v_pk_add_f32 v[104:105], v[104:105], v[112:113]
	v_lshlrev_b32_e32 v114, 16, v9
	v_and_b32_e32 v115, 0xffff0000, v9
	v_pk_add_f32 v[106:107], v[106:107], v[114:115]
	s_waitcnt vmcnt(13)
	v_lshlrev_b32_e32 v108, 16, v10
	v_and_b32_e32 v109, 0xffff0000, v10
	v_pk_add_f32 v[74:75], v[74:75], v[108:109]
	v_lshlrev_b32_e32 v110, 16, v11
	v_and_b32_e32 v111, 0xffff0000, v11
	v_pk_add_f32 v[76:77], v[76:77], v[110:111]
	v_lshlrev_b32_e32 v112, 16, v12
	v_and_b32_e32 v113, 0xffff0000, v12
	v_pk_add_f32 v[104:105], v[104:105], v[112:113]
	v_lshlrev_b32_e32 v114, 16, v13
	v_and_b32_e32 v115, 0xffff0000, v13
	v_pk_add_f32 v[106:107], v[106:107], v[114:115]
	s_waitcnt vmcnt(12)
	v_lshlrev_b32_e32 v108, 16, v14
	v_and_b32_e32 v109, 0xffff0000, v14
	v_pk_add_f32 v[74:75], v[74:75], v[108:109]
	v_lshlrev_b32_e32 v110, 16, v15
	v_and_b32_e32 v111, 0xffff0000, v15
	v_pk_add_f32 v[76:77], v[76:77], v[110:111]
	v_lshlrev_b32_e32 v112, 16, v16
	v_and_b32_e32 v113, 0xffff0000, v16
	v_pk_add_f32 v[104:105], v[104:105], v[112:113]
	v_lshlrev_b32_e32 v114, 16, v17
	v_and_b32_e32 v115, 0xffff0000, v17
	v_pk_add_f32 v[106:107], v[106:107], v[114:115]
	s_waitcnt vmcnt(11)
	v_lshlrev_b32_e32 v108, 16, v18
	v_and_b32_e32 v109, 0xffff0000, v18
	v_pk_add_f32 v[74:75], v[74:75], v[108:109]
	v_lshlrev_b32_e32 v110, 16, v19
	v_and_b32_e32 v111, 0xffff0000, v19
	v_pk_add_f32 v[76:77], v[76:77], v[110:111]
	v_lshlrev_b32_e32 v112, 16, v20
	v_and_b32_e32 v113, 0xffff0000, v20
	v_pk_add_f32 v[104:105], v[104:105], v[112:113]
	v_lshlrev_b32_e32 v114, 16, v21
	v_and_b32_e32 v115, 0xffff0000, v21
	v_pk_add_f32 v[106:107], v[106:107], v[114:115]
	s_waitcnt vmcnt(10)
	v_lshlrev_b32_e32 v108, 16, v22
	v_and_b32_e32 v109, 0xffff0000, v22
	v_pk_add_f32 v[74:75], v[74:75], v[108:109]
	v_lshlrev_b32_e32 v110, 16, v23
	v_and_b32_e32 v111, 0xffff0000, v23
	v_pk_add_f32 v[76:77], v[76:77], v[110:111]
	v_lshlrev_b32_e32 v112, 16, v24
	v_and_b32_e32 v113, 0xffff0000, v24
	v_pk_add_f32 v[104:105], v[104:105], v[112:113]
	v_lshlrev_b32_e32 v114, 16, v25
	v_and_b32_e32 v115, 0xffff0000, v25
	v_pk_add_f32 v[106:107], v[106:107], v[114:115]
	s_waitcnt vmcnt(9)
	v_lshlrev_b32_e32 v108, 16, v26
	v_and_b32_e32 v109, 0xffff0000, v26
	v_pk_add_f32 v[74:75], v[74:75], v[108:109]
	v_lshlrev_b32_e32 v110, 16, v27
	v_and_b32_e32 v111, 0xffff0000, v27
	v_pk_add_f32 v[76:77], v[76:77], v[110:111]
	v_lshlrev_b32_e32 v112, 16, v28
	v_and_b32_e32 v113, 0xffff0000, v28
	v_pk_add_f32 v[104:105], v[104:105], v[112:113]
	v_lshlrev_b32_e32 v114, 16, v29
	v_and_b32_e32 v115, 0xffff0000, v29
	v_pk_add_f32 v[106:107], v[106:107], v[114:115]
	s_waitcnt vmcnt(8)
	v_lshlrev_b32_e32 v108, 16, v30
	v_and_b32_e32 v109, 0xffff0000, v30
	v_pk_add_f32 v[74:75], v[74:75], v[108:109]
	v_lshlrev_b32_e32 v110, 16, v31
	v_and_b32_e32 v111, 0xffff0000, v31
	v_pk_add_f32 v[76:77], v[76:77], v[110:111]
	v_lshlrev_b32_e32 v112, 16, v32
	v_and_b32_e32 v113, 0xffff0000, v32
	v_pk_add_f32 v[104:105], v[104:105], v[112:113]
	v_lshlrev_b32_e32 v114, 16, v33
	v_and_b32_e32 v115, 0xffff0000, v33
	v_pk_add_f32 v[106:107], v[106:107], v[114:115]
	s_waitcnt vmcnt(7)
	v_lshlrev_b32_e32 v108, 16, v34
	v_and_b32_e32 v109, 0xffff0000, v34
	v_pk_add_f32 v[74:75], v[74:75], v[108:109]
	v_lshlrev_b32_e32 v110, 16, v35
	v_and_b32_e32 v111, 0xffff0000, v35
	v_pk_add_f32 v[76:77], v[76:77], v[110:111]
	v_lshlrev_b32_e32 v112, 16, v36
	v_and_b32_e32 v113, 0xffff0000, v36
	v_pk_add_f32 v[104:105], v[104:105], v[112:113]
	v_lshlrev_b32_e32 v114, 16, v37
	v_and_b32_e32 v115, 0xffff0000, v37
	v_pk_add_f32 v[106:107], v[106:107], v[114:115]
	s_waitcnt vmcnt(6)
	v_lshlrev_b32_e32 v108, 16, v38
	v_and_b32_e32 v109, 0xffff0000, v38
	v_pk_add_f32 v[74:75], v[74:75], v[108:109]
	v_lshlrev_b32_e32 v110, 16, v39
	v_and_b32_e32 v111, 0xffff0000, v39
	v_pk_add_f32 v[76:77], v[76:77], v[110:111]
	v_lshlrev_b32_e32 v112, 16, v40
	v_and_b32_e32 v113, 0xffff0000, v40
	v_pk_add_f32 v[104:105], v[104:105], v[112:113]
	v_lshlrev_b32_e32 v114, 16, v41
	v_and_b32_e32 v115, 0xffff0000, v41
	v_pk_add_f32 v[106:107], v[106:107], v[114:115]
	s_waitcnt vmcnt(5)
	v_lshlrev_b32_e32 v108, 16, v42
	v_and_b32_e32 v109, 0xffff0000, v42
	v_pk_add_f32 v[74:75], v[74:75], v[108:109]
	v_lshlrev_b32_e32 v110, 16, v43
	v_and_b32_e32 v111, 0xffff0000, v43
	v_pk_add_f32 v[76:77], v[76:77], v[110:111]
	v_lshlrev_b32_e32 v112, 16, v44
	v_and_b32_e32 v113, 0xffff0000, v44
	v_pk_add_f32 v[104:105], v[104:105], v[112:113]
	v_lshlrev_b32_e32 v114, 16, v45
	v_and_b32_e32 v115, 0xffff0000, v45
	v_pk_add_f32 v[106:107], v[106:107], v[114:115]
	s_waitcnt vmcnt(4)
	v_lshlrev_b32_e32 v108, 16, v46
	v_and_b32_e32 v109, 0xffff0000, v46
	v_pk_add_f32 v[74:75], v[74:75], v[108:109]
	v_lshlrev_b32_e32 v110, 16, v47
	v_and_b32_e32 v111, 0xffff0000, v47
	v_pk_add_f32 v[76:77], v[76:77], v[110:111]
	v_lshlrev_b32_e32 v112, 16, v48
	v_and_b32_e32 v113, 0xffff0000, v48
	v_pk_add_f32 v[104:105], v[104:105], v[112:113]
	v_lshlrev_b32_e32 v114, 16, v49
	v_and_b32_e32 v115, 0xffff0000, v49
	v_pk_add_f32 v[106:107], v[106:107], v[114:115]
	s_waitcnt vmcnt(3)
	v_lshlrev_b32_e32 v108, 16, v50
	v_and_b32_e32 v109, 0xffff0000, v50
	v_pk_add_f32 v[74:75], v[74:75], v[108:109]
	v_lshlrev_b32_e32 v110, 16, v51
	v_and_b32_e32 v111, 0xffff0000, v51
	v_pk_add_f32 v[76:77], v[76:77], v[110:111]
	v_lshlrev_b32_e32 v112, 16, v52
	v_and_b32_e32 v113, 0xffff0000, v52
	v_pk_add_f32 v[104:105], v[104:105], v[112:113]
	v_lshlrev_b32_e32 v114, 16, v53
	v_and_b32_e32 v115, 0xffff0000, v53
	v_pk_add_f32 v[106:107], v[106:107], v[114:115]
	s_waitcnt vmcnt(2)
	v_lshlrev_b32_e32 v108, 16, v54
	v_and_b32_e32 v109, 0xffff0000, v54
	v_pk_add_f32 v[74:75], v[74:75], v[108:109]
	v_lshlrev_b32_e32 v110, 16, v55
	v_and_b32_e32 v111, 0xffff0000, v55
	v_pk_add_f32 v[76:77], v[76:77], v[110:111]
	v_lshlrev_b32_e32 v112, 16, v56
	v_and_b32_e32 v113, 0xffff0000, v56
	v_pk_add_f32 v[104:105], v[104:105], v[112:113]
	v_lshlrev_b32_e32 v114, 16, v57
	v_and_b32_e32 v115, 0xffff0000, v57
	v_pk_add_f32 v[106:107], v[106:107], v[114:115]
	s_waitcnt vmcnt(1)
	v_lshlrev_b32_e32 v108, 16, v58
	v_and_b32_e32 v109, 0xffff0000, v58
	v_pk_add_f32 v[74:75], v[74:75], v[108:109]
	v_lshlrev_b32_e32 v110, 16, v59
	v_and_b32_e32 v111, 0xffff0000, v59
	v_pk_add_f32 v[76:77], v[76:77], v[110:111]
	v_lshlrev_b32_e32 v112, 16, v60
	v_and_b32_e32 v113, 0xffff0000, v60
	v_pk_add_f32 v[104:105], v[104:105], v[112:113]
	v_lshlrev_b32_e32 v114, 16, v61
	v_and_b32_e32 v115, 0xffff0000, v61
	v_pk_add_f32 v[106:107], v[106:107], v[114:115]
	s_waitcnt vmcnt(0)
	v_lshlrev_b32_e32 v108, 16, v62
	v_and_b32_e32 v109, 0xffff0000, v62
	v_pk_add_f32 v[74:75], v[74:75], v[108:109]
	v_lshlrev_b32_e32 v110, 16, v63
	v_and_b32_e32 v111, 0xffff0000, v63
	v_pk_add_f32 v[76:77], v[76:77], v[110:111]
	v_lshlrev_b32_e32 v112, 16, v64
	v_and_b32_e32 v113, 0xffff0000, v64
	v_pk_add_f32 v[104:105], v[104:105], v[112:113]
	v_lshlrev_b32_e32 v114, 16, v65
	v_and_b32_e32 v115, 0xffff0000, v65
	v_pk_add_f32 v[106:107], v[106:107], v[114:115]
	v_mov_b64_e32 v[70:71], v[104:105]
	v_mov_b64_e32 v[72:73], v[106:107]

.LBB0_1507:
	s_add_u32 s58, s70, 0x13000
	s_addc_u32 s59, s71, 0
	s_lshl_b32 s6, s6, 5
	s_mov_b64 s[10:11], 0x80
	s_and_b32 s6, s6, 0x60
	s_add_i32 m0, s49, 0x18000
	v_lshl_add_u64 v[10:11], v[10:11], 0, s[10:11]
	s_lshl_b32 s14, s0, 13
	s_lshl_b32 s15, s6, 7
	s_waitcnt vmcnt(2)
	s_barrier
	global_load_lds_dwordx4 v[10:11], off
	v_lshl_add_u64 v[6:7], v[6:7], 0, s[10:11]
	s_add_i32 m0, s49, 0x1a000
	s_add_i32 s60, s49, 0x8000
	s_add_i32 s61, s49, 0xa000
	global_load_lds_dwordx4 v[6:7], off
	v_lshl_add_u64 v[6:7], v[8:9], 0, s[10:11]
	s_mov_b32 m0, s60
	s_add_u32 s12, s34, 0x160080
	global_load_lds_dwordx4 v[6:7], off
	v_lshl_add_u64 v[4:5], v[4:5], 0, s[10:11]
	s_mov_b32 m0, s61
	s_addc_u32 s13, s35, 0
	global_load_lds_dwordx4 v[4:5], off
	s_add_i32 m0, s49, 0x1c000
	v_lshl_add_u64 v[4:5], s[12:13], 0, v[132:133]
	global_load_lds_dwordx4 v[4:5], off
	v_lshl_add_u64 v[4:5], s[12:13], 0, v[136:137]
	s_add_i32 m0, s49, 0x1e000
	v_and_b32_e32 v3, 15, v143
	global_load_lds_dwordx4 v[4:5], off
	v_lshlrev_b32_e32 v4, 1, v14
	v_lshlrev_b32_e32 v5, 2, v143
	v_lshl_or_b32 v1, s0, 6, v3
	v_lshl_or_b32 v3, v3, 6, v4
	v_and_b32_e32 v5, 32, v5
	v_bitop3_b32 v6, v3, s14, v5 bitop3:0xde
	v_lshlrev_b32_e32 v3, 6, v143
	s_movk_i32 s0, 0x3c0
	s_cmpk_lt_u32 s3, 0x100
	v_and_or_b32 v3, v3, s0, v4
	s_cselect_b64 s[12:13], -1, 0
	s_cmpk_lt_i32 s2, 0x100
	v_bitop3_b32 v150, s15, v3, v5 bitop3:0xf6
	s_cselect_b64 s[14:15], -1, 0
	s_ashr_i32 s67, s2, 4
	s_and_b32 s76, s2, 15
	s_ashr_i32 s2, s2, 7
	v_readlane_b32 s16, v242, 53
	s_add_i32 s77, s2, 32
	s_mul_i32 s2, s76, 4
	v_mov_b32_e32 v3, v133
	v_readlane_b32 s17, v242, 54
	s_and_b32 s78, s67, 7
	s_add_i32 s2, s2, 24
	s_waitcnt vmcnt(6)
	v_lshl_add_u64 v[138:139], s[16:17], 0, v[2:3]
	s_cmp_lt_u32 s76, 12
	s_mul_i32 s3, s76, 6
	v_add_u16_e32 v2, v12, v13
	s_cselect_b32 s79, 6, 4
	s_cselect_b32 s16, s3, s2
	v_lshrrev_b16_e32 v2, 1, v2
	s_add_i32 s80, 0, 0x10000
	s_add_i32 s81, 0, 0x14000
	s_sext_i32_i8 s43, s1
	s_mov_b32 s62, 0x18000
	s_mov_b32 s63, 0x1a000
	s_mov_b32 s33, 0x8000
	s_mov_b32 s65, 0xa000
	s_mov_b32 s66, 0x1c000
	v_cmp_eq_u32_e64 s[0:1], 0, v143
	v_or_b32_e32 v151, s6, v14
	v_add_lshl_u32 v140, v15, v2, 1
	v_mov_b32_e32 v141, v133
	v_add_lshl_u32 v144, v16, v2, 1
	v_mov_b32_e32 v145, v133
	s_mov_b64 s[2:3], -1
	s_movk_i32 s44, 0x58
	s_mov_b32 s88, -1
	v_add_u32_e32 v152, s80, v150
	v_add_u32_e32 v153, s81, v150
	v_add_u32_e32 v154, 0, v6
	s_mov_b32 s82, 0xc000
	s_mov_b32 s83, 0xe000
	s_mov_b32 s84, 0x80000
	s_mov_b32 s85, 0xa0000
	s_mov_b64 s[18:19], 0x80000
	s_mov_b64 s[20:21], 0x90000
	s_mov_b32 s87, 0x90000
	s_mov_b64 s[22:23], 0xa0000
	s_mov_b64 s[24:25], 0xb0000
	s_mov_b32 s6, 0
	s_barrier
	s_branch .LBB0_1510

.LBB0_1518:
	v_lshl_add_u32 v148, s42, 8, v1
	v_lshl_or_b32 v146, s43, 8, v151
	s_mov_b64 s[30:31], -1
	s_cmp_gt_i32 s88, -1
	v_cvt_pk_bf16_f32 v66, v66, v67
	v_cvt_pk_bf16_f32 v67, v68, v69
	v_cvt_pk_bf16_f32 v68, v126, v127
	v_cvt_pk_bf16_f32 v69, v128, v129
	v_cvt_pk_bf16_f32 v62, v62, v63
	v_cvt_pk_bf16_f32 v63, v64, v65
	v_cvt_pk_bf16_f32 v64, v58, v59
	v_cvt_pk_bf16_f32 v65, v60, v61
	v_cvt_pk_bf16_f32 v58, v122, v123
	v_cvt_pk_bf16_f32 v59, v124, v125
	v_cvt_pk_bf16_f32 v60, v118, v119
	v_cvt_pk_bf16_f32 v61, v120, v121
	v_cvt_pk_bf16_f32 v54, v54, v55
	v_cvt_pk_bf16_f32 v55, v56, v57
	v_cvt_pk_bf16_f32 v56, v50, v51
	v_cvt_pk_bf16_f32 v57, v52, v53
	v_cvt_pk_bf16_f32 v50, v114, v115
	v_cvt_pk_bf16_f32 v51, v116, v117
	v_cvt_pk_bf16_f32 v52, v110, v111
	v_cvt_pk_bf16_f32 v53, v112, v113
	v_cvt_pk_bf16_f32 v46, v46, v47
	v_cvt_pk_bf16_f32 v47, v48, v49
	v_cvt_pk_bf16_f32 v48, v42, v43
	v_cvt_pk_bf16_f32 v49, v44, v45
	v_cvt_pk_bf16_f32 v42, v106, v107
	v_cvt_pk_bf16_f32 v43, v108, v109
	v_cvt_pk_bf16_f32 v44, v102, v103
	v_cvt_pk_bf16_f32 v45, v104, v105
	v_cvt_pk_bf16_f32 v38, v38, v39
	v_cvt_pk_bf16_f32 v39, v40, v41
	v_cvt_pk_bf16_f32 v40, v98, v99
	v_cvt_pk_bf16_f32 v41, v100, v101
	v_cvt_pk_bf16_f32 v34, v34, v35
	v_cvt_pk_bf16_f32 v35, v36, v37
	v_cvt_pk_bf16_f32 v36, v94, v95
	v_cvt_pk_bf16_f32 v37, v96, v97
	v_cvt_pk_bf16_f32 v30, v30, v31
	v_cvt_pk_bf16_f32 v31, v32, v33
	v_cvt_pk_bf16_f32 v32, v26, v27
	v_cvt_pk_bf16_f32 v33, v28, v29
	v_cvt_pk_bf16_f32 v26, v90, v91
	v_cvt_pk_bf16_f32 v27, v92, v93
	v_cvt_pk_bf16_f32 v28, v86, v87
	v_cvt_pk_bf16_f32 v29, v88, v89
	v_cvt_pk_bf16_f32 v22, v22, v23
	v_cvt_pk_bf16_f32 v23, v24, v25
	v_cvt_pk_bf16_f32 v24, v18, v19
	v_cvt_pk_bf16_f32 v25, v20, v21
	v_cvt_pk_bf16_f32 v18, v82, v83
	v_cvt_pk_bf16_f32 v19, v84, v85
	v_cvt_pk_bf16_f32 v20, v78, v79
	v_cvt_pk_bf16_f32 v21, v80, v81
	v_cvt_pk_bf16_f32 v14, v14, v15
	v_cvt_pk_bf16_f32 v15, v16, v17
	v_cvt_pk_bf16_f32 v16, v10, v11
	v_cvt_pk_bf16_f32 v17, v12, v13
	v_cvt_pk_bf16_f32 v10, v74, v75
	v_cvt_pk_bf16_f32 v11, v76, v77
	v_cvt_pk_bf16_f32 v12, v70, v71
	v_cvt_pk_bf16_f32 v13, v72, v73
	s_cbranch_scc0 .LBB0_1532
	s_lshl_b32 s30, s6, 4
	s_add_i32 s34, s30, s88
	s_ashr_i32 s35, s34, 31
	s_lshl_b64 s[34:35], s[34:35], 17
	v_lshl_add_u64 v[74:75], v[138:139], 0, s[34:35]
	s_movk_i32 s17, 0x2000
	v_add_co_u32_e32 v70, vcc, s17, v74
	s_mov_b32 s17, 0x10000
	s_nop 0
	v_addc_co_u32_e32 v71, vcc, 0, v75, vcc
	global_store_dwordx4 v[70:71], v[62:65], off
	v_add_co_u32_e32 v70, vcc, s56, v74
	global_store_dwordx4 v[74:75], v[66:69], off
	s_nop 0
	v_addc_co_u32_e32 v71, vcc, 0, v75, vcc
	global_store_dwordx4 v[70:71], v[58:61], off
	v_add_co_u32_e32 v70, vcc, s57, v74
	v_cvt_pk_bf16_f32 v72, v2, v3
	s_nop 0
	v_addc_co_u32_e32 v71, vcc, 0, v75, vcc
	global_store_dwordx4 v[70:71], v[54:57], off
	v_add_co_u32_e32 v70, vcc, s33, v74
	v_cvt_pk_bf16_f32 v73, v4, v5
	s_nop 0
	v_addc_co_u32_e32 v71, vcc, 0, v75, vcc
	global_store_dwordx4 v[70:71], v[50:53], off
	v_add_co_u32_e32 v70, vcc, s65, v74
	s_nop 1
	v_addc_co_u32_e32 v71, vcc, 0, v75, vcc
	global_store_dwordx4 v[70:71], v[46:49], off
	v_add_co_u32_e32 v70, vcc, s82, v74
	s_nop 1
	v_addc_co_u32_e32 v71, vcc, 0, v75, vcc
	global_store_dwordx4 v[70:71], v[42:45], off
	v_add_co_u32_e32 v70, vcc, s83, v74
	s_nop 1
	v_addc_co_u32_e32 v71, vcc, 0, v75, vcc
	global_store_dwordx4 v[70:71], v[38:41], off
	v_add_co_u32_e32 v70, vcc, s17, v74
	s_nop 1
	v_addc_co_u32_e32 v71, vcc, 0, v75, vcc
	global_store_dwordx4 v[70:71], v[34:37], off
	v_add_co_u32_e32 v70, vcc, s53, v74
	s_nop 1
	v_addc_co_u32_e32 v71, vcc, 0, v75, vcc
	global_store_dwordx4 v[70:71], v[30:33], off
	v_add_co_u32_e32 v70, vcc, s54, v74
	s_nop 1
	v_addc_co_u32_e32 v71, vcc, 0, v75, vcc
	global_store_dwordx4 v[70:71], v[26:29], off
	v_add_co_u32_e32 v70, vcc, s55, v74
	s_nop 1
	v_addc_co_u32_e32 v71, vcc, 0, v75, vcc
	global_store_dwordx4 v[70:71], v[22:25], off
	v_add_co_u32_e32 v70, vcc, s62, v74
	s_nop 1
	v_addc_co_u32_e32 v71, vcc, 0, v75, vcc
	global_store_dwordx4 v[70:71], v[18:21], off
	v_add_co_u32_e32 v70, vcc, s63, v74
	s_nop 1
	v_addc_co_u32_e32 v71, vcc, 0, v75, vcc
	global_store_dwordx4 v[70:71], v[14:17], off
	v_add_co_u32_e32 v70, vcc, s66, v74
	s_nop 1
	v_addc_co_u32_e32 v71, vcc, 0, v75, vcc
	v_add_co_u32_e32 v74, vcc, 0x1e000, v74
	global_store_dwordx4 v[70:71], v[10:13], off
	v_cvt_pk_bf16_f32 v70, v6, v7
	v_cvt_pk_bf16_f32 v71, v8, v9
	v_addc_co_u32_e32 v75, vcc, 0, v75, vcc
	global_store_dwordx4 v[74:75], v[70:73], off
	s_waitcnt vmcnt(0)
	s_waitcnt vmcnt(0)
	s_barrier
	s_and_saveexec_b64 s[34:35], s[0:1]
	s_cbranch_execz .LBB0_1531
	s_lshl_b32 s36, s6, 6
	s_mov_b64 s[42:43], exec
	s_ashr_i32 s37, s36, 31
	s_lshl_b64 s[36:37], s[36:37], 2
	buffer_wbl2 sc1
	s_waitcnt vmcnt(0)
	v_mbcnt_lo_u32_b32 v70, s42, 0
	s_add_u32 s36, s58, s36
	v_mbcnt_hi_u32_b32 v70, s43, v70
	s_addc_u32 s37, s59, s37
	v_cmp_eq_u32_e32 vcc, 0, v70
	s_and_saveexec_b64 s[44:45], vcc
	s_cbranch_execz .LBB0_1522
	s_bcnt1_i32_b64 s6, s[42:43]
	v_mov_b32_e32 v70, s6
	global_atomic_add v133, v70, s[36:37]

.LBB0_1524:
	global_load_dword v70, v133, s[36:37] sc1
	s_mov_b64 s[42:43], -1
	s_waitcnt vmcnt(0)
	v_cmp_lt_u32_e32 vcc, 15, v70
	s_cbranch_vccnz .LBB0_1523
	s_sleep 2
	global_load_dword v70, v133, s[36:37] sc1
	s_waitcnt vmcnt(0)
	v_cmp_gt_u32_e32 vcc, 16, v70
	s_cbranch_vccz .LBB0_1523
	s_sleep 2
	global_load_dword v70, v133, s[36:37] sc1
	s_waitcnt vmcnt(0)
	v_cmp_gt_u32_e32 vcc, 16, v70
	s_cbranch_vccz .LBB0_1523
	s_sleep 2
	global_load_dword v70, v133, s[36:37] sc1
	s_waitcnt vmcnt(0)
	v_cmp_gt_u32_e32 vcc, 16, v70
	s_cbranch_vccz .LBB0_1523
	s_sleep 2
	global_load_dword v70, v133, s[36:37] sc1
	s_waitcnt vmcnt(0)
	v_cmp_gt_u32_e32 vcc, 16, v70
	s_cbranch_vccz .LBB0_1523
	s_add_i32 s6, s6, -5
	s_cmp_eq_u32 s6, 0
	s_cselect_b64 s[42:43], -1, 0
	s_sleep 2
	s_branch .LBB0_1523

.LBB0_1531:
	s_or_b64 exec, exec, s[34:35]
	s_ashr_i32 s31, s30, 31
	s_lshl_b64 s[30:31], s[30:31], 17
	v_lshl_add_u64 v[70:71], v[138:139], 0, s[30:31]
	s_lshl_b32 s30, s88, 13
	s_mov_b32 s31, 0
	v_lshl_add_u64 v[70:71], v[70:71], 0, s[30:31]
	s_mov_b64 s[30:31], 0x20000
	s_barrier
	global_load_dwordx4 v[2:5], v[70:71], off
	v_lshl_add_u64 v[72:73], v[70:71], 0, s[30:31]
	global_load_dwordx4 v[6:9], v[72:73], off
	v_lshl_add_u64 v[72:73], v[72:73], 0, s[30:31]
	global_load_dwordx4 v[10:13], v[72:73], off
	v_lshl_add_u64 v[72:73], v[72:73], 0, s[30:31]
	global_load_dwordx4 v[14:17], v[72:73], off
	v_lshl_add_u64 v[72:73], v[72:73], 0, s[30:31]
	global_load_dwordx4 v[18:21], v[72:73], off
	v_lshl_add_u64 v[72:73], v[72:73], 0, s[30:31]
	global_load_dwordx4 v[22:25], v[72:73], off
	v_lshl_add_u64 v[72:73], v[72:73], 0, s[30:31]
	global_load_dwordx4 v[26:29], v[72:73], off
	v_lshl_add_u64 v[72:73], v[72:73], 0, s[30:31]
	global_load_dwordx4 v[30:33], v[72:73], off
	v_lshl_add_u64 v[72:73], v[72:73], 0, s[30:31]
	global_load_dwordx4 v[34:37], v[72:73], off
	v_lshl_add_u64 v[72:73], v[72:73], 0, s[30:31]
	global_load_dwordx4 v[38:41], v[72:73], off
	v_lshl_add_u64 v[72:73], v[72:73], 0, s[30:31]
	global_load_dwordx4 v[42:45], v[72:73], off
	v_lshl_add_u64 v[72:73], v[72:73], 0, s[30:31]
	global_load_dwordx4 v[46:49], v[72:73], off
	v_lshl_add_u64 v[72:73], v[72:73], 0, s[30:31]
	global_load_dwordx4 v[50:53], v[72:73], off
	v_lshl_add_u64 v[72:73], v[72:73], 0, s[30:31]
	global_load_dwordx4 v[54:57], v[72:73], off
	v_lshl_add_u64 v[72:73], v[72:73], 0, s[30:31]
	global_load_dwordx4 v[58:61], v[72:73], off
	v_lshl_add_u64 v[72:73], v[72:73], 0, s[30:31]
	global_load_dwordx4 v[62:65], v[72:73], off
	s_lshl_b32 s6, s88, 4
	s_and_b32 s6, s6, 0x80
	v_add_u32_e32 v160, s6, v148
	s_lshl_b32 s6, s88, 3
	s_and_b32 s6, s6, 48
	v_or_b32_e32 v160, s6, v160
	v_ashrrev_i32_e32 v161, 31, v160
	v_ashrrev_i32_e32 v147, 31, v146
	v_lshlrev_b64 v[102:103], 12, v[160:161]
	s_and_b32 s6, s88, 1
	s_lshl_b32 s6, s6, 8
	s_sub_u32 s30, s6, 0x100
	s_subb_u32 s31, 0, 0
	v_lshl_add_u64 v[102:103], v[102:103], 0, s[30:31]
	s_mov_b64 s[30:31], 0
	s_waitcnt vmcnt(15)
	v_lshlrev_b32_e32 v74, 16, v2
	v_and_b32_e32 v75, 0xffff0000, v2
	v_lshlrev_b32_e32 v76, 16, v3
	v_and_b32_e32 v77, 0xffff0000, v3
	v_lshlrev_b32_e32 v104, 16, v4
	v_and_b32_e32 v105, 0xffff0000, v4
	v_lshlrev_b32_e32 v106, 16, v5
	v_and_b32_e32 v107, 0xffff0000, v5
	s_waitcnt vmcnt(14)
	v_lshlrev_b32_e32 v108, 16, v6
	v_and_b32_e32 v109, 0xffff0000, v6
	v_pk_add_f32 v[74:75], v[74:75], v[108:109]
	v_lshlrev_b32_e32 v110, 16, v7
	v_and_b32_e32 v111, 0xffff0000, v7
	v_pk_add_f32 v[76:77], v[76:77], v[110:111]
	v_lshlrev_b32_e32 v112, 16, v8
	v_and_b32_e32 v113, 0xffff0000, v8
	v_pk_add_f32 v[104:105], v[104:105], v[112:113]
	v_lshlrev_b32_e32 v114, 16, v9
	v_and_b32_e32 v115, 0xffff0000, v9
	v_pk_add_f32 v[106:107], v[106:107], v[114:115]
	s_waitcnt vmcnt(13)
	v_lshlrev_b32_e32 v108, 16, v10
	v_and_b32_e32 v109, 0xffff0000, v10
	v_pk_add_f32 v[74:75], v[74:75], v[108:109]
	v_lshlrev_b32_e32 v110, 16, v11
	v_and_b32_e32 v111, 0xffff0000, v11
	v_pk_add_f32 v[76:77], v[76:77], v[110:111]
	v_lshlrev_b32_e32 v112, 16, v12
	v_and_b32_e32 v113, 0xffff0000, v12
	v_pk_add_f32 v[104:105], v[104:105], v[112:113]
	v_lshlrev_b32_e32 v114, 16, v13
	v_and_b32_e32 v115, 0xffff0000, v13
	v_pk_add_f32 v[106:107], v[106:107], v[114:115]
	s_waitcnt vmcnt(12)
	v_lshlrev_b32_e32 v108, 16, v14
	v_and_b32_e32 v109, 0xffff0000, v14
	v_pk_add_f32 v[74:75], v[74:75], v[108:109]
	v_lshlrev_b32_e32 v110, 16, v15
	v_and_b32_e32 v111, 0xffff0000, v15
	v_pk_add_f32 v[76:77], v[76:77], v[110:111]
	v_lshlrev_b32_e32 v112, 16, v16
	v_and_b32_e32 v113, 0xffff0000, v16
	v_pk_add_f32 v[104:105], v[104:105], v[112:113]
	v_lshlrev_b32_e32 v114, 16, v17
	v_and_b32_e32 v115, 0xffff0000, v17
	v_pk_add_f32 v[106:107], v[106:107], v[114:115]
	s_waitcnt vmcnt(11)
	v_lshlrev_b32_e32 v108, 16, v18
	v_and_b32_e32 v109, 0xffff0000, v18
	v_pk_add_f32 v[74:75], v[74:75], v[108:109]
	v_lshlrev_b32_e32 v110, 16, v19
	v_and_b32_e32 v111, 0xffff0000, v19
	v_pk_add_f32 v[76:77], v[76:77], v[110:111]
	v_lshlrev_b32_e32 v112, 16, v20
	v_and_b32_e32 v113, 0xffff0000, v20
	v_pk_add_f32 v[104:105], v[104:105], v[112:113]
	v_lshlrev_b32_e32 v114, 16, v21
	v_and_b32_e32 v115, 0xffff0000, v21
	v_pk_add_f32 v[106:107], v[106:107], v[114:115]
	s_waitcnt vmcnt(10)
	v_lshlrev_b32_e32 v108, 16, v22
	v_and_b32_e32 v109, 0xffff0000, v22
	v_pk_add_f32 v[74:75], v[74:75], v[108:109]
	v_lshlrev_b32_e32 v110, 16, v23
	v_and_b32_e32 v111, 0xffff0000, v23
	v_pk_add_f32 v[76:77], v[76:77], v[110:111]
	v_lshlrev_b32_e32 v112, 16, v24
	v_and_b32_e32 v113, 0xffff0000, v24
	v_pk_add_f32 v[104:105], v[104:105], v[112:113]
	v_lshlrev_b32_e32 v114, 16, v25
	v_and_b32_e32 v115, 0xffff0000, v25
	v_pk_add_f32 v[106:107], v[106:107], v[114:115]
	s_waitcnt vmcnt(9)
	v_lshlrev_b32_e32 v108, 16, v26
	v_and_b32_e32 v109, 0xffff0000, v26
	v_pk_add_f32 v[74:75], v[74:75], v[108:109]
	v_lshlrev_b32_e32 v110, 16, v27
	v_and_b32_e32 v111, 0xffff0000, v27
	v_pk_add_f32 v[76:77], v[76:77], v[110:111]
	v_lshlrev_b32_e32 v112, 16, v28
	v_and_b32_e32 v113, 0xffff0000, v28
	v_pk_add_f32 v[104:105], v[104:105], v[112:113]
	v_lshlrev_b32_e32 v114, 16, v29
	v_and_b32_e32 v115, 0xffff0000, v29
	v_pk_add_f32 v[106:107], v[106:107], v[114:115]
	s_waitcnt vmcnt(8)
	v_lshlrev_b32_e32 v108, 16, v30
	v_and_b32_e32 v109, 0xffff0000, v30
	v_pk_add_f32 v[74:75], v[74:75], v[108:109]
	v_lshlrev_b32_e32 v110, 16, v31
	v_and_b32_e32 v111, 0xffff0000, v31
	v_pk_add_f32 v[76:77], v[76:77], v[110:111]
	v_lshlrev_b32_e32 v112, 16, v32
	v_and_b32_e32 v113, 0xffff0000, v32
	v_pk_add_f32 v[104:105], v[104:105], v[112:113]
	v_lshlrev_b32_e32 v114, 16, v33
	v_and_b32_e32 v115, 0xffff0000, v33
	v_pk_add_f32 v[106:107], v[106:107], v[114:115]
	s_waitcnt vmcnt(7)
	v_lshlrev_b32_e32 v108, 16, v34
	v_and_b32_e32 v109, 0xffff0000, v34
	v_pk_add_f32 v[74:75], v[74:75], v[108:109]
	v_lshlrev_b32_e32 v110, 16, v35
	v_and_b32_e32 v111, 0xffff0000, v35
	v_pk_add_f32 v[76:77], v[76:77], v[110:111]
	v_lshlrev_b32_e32 v112, 16, v36
	v_and_b32_e32 v113, 0xffff0000, v36
	v_pk_add_f32 v[104:105], v[104:105], v[112:113]
	v_lshlrev_b32_e32 v114, 16, v37
	v_and_b32_e32 v115, 0xffff0000, v37
	v_pk_add_f32 v[106:107], v[106:107], v[114:115]
	s_waitcnt vmcnt(6)
	v_lshlrev_b32_e32 v108, 16, v38
	v_and_b32_e32 v109, 0xffff0000, v38
	v_pk_add_f32 v[74:75], v[74:75], v[108:109]
	v_lshlrev_b32_e32 v110, 16, v39
	v_and_b32_e32 v111, 0xffff0000, v39
	v_pk_add_f32 v[76:77], v[76:77], v[110:111]
	v_lshlrev_b32_e32 v112, 16, v40
	v_and_b32_e32 v113, 0xffff0000, v40
	v_pk_add_f32 v[104:105], v[104:105], v[112:113]
	v_lshlrev_b32_e32 v114, 16, v41
	v_and_b32_e32 v115, 0xffff0000, v41
	v_pk_add_f32 v[106:107], v[106:107], v[114:115]
	s_waitcnt vmcnt(5)
	v_lshlrev_b32_e32 v108, 16, v42
	v_and_b32_e32 v109, 0xffff0000, v42
	v_pk_add_f32 v[74:75], v[74:75], v[108:109]
	v_lshlrev_b32_e32 v110, 16, v43
	v_and_b32_e32 v111, 0xffff0000, v43
	v_pk_add_f32 v[76:77], v[76:77], v[110:111]
	v_lshlrev_b32_e32 v112, 16, v44
	v_and_b32_e32 v113, 0xffff0000, v44
	v_pk_add_f32 v[104:105], v[104:105], v[112:113]
	v_lshlrev_b32_e32 v114, 16, v45
	v_and_b32_e32 v115, 0xffff0000, v45
	v_pk_add_f32 v[106:107], v[106:107], v[114:115]
	s_waitcnt vmcnt(4)
	v_lshlrev_b32_e32 v108, 16, v46
	v_and_b32_e32 v109, 0xffff0000, v46
	v_pk_add_f32 v[74:75], v[74:75], v[108:109]
	v_lshlrev_b32_e32 v110, 16, v47
	v_and_b32_e32 v111, 0xffff0000, v47
	v_pk_add_f32 v[76:77], v[76:77], v[110:111]
	v_lshlrev_b32_e32 v112, 16, v48
	v_and_b32_e32 v113, 0xffff0000, v48
	v_pk_add_f32 v[104:105], v[104:105], v[112:113]
	v_lshlrev_b32_e32 v114, 16, v49
	v_and_b32_e32 v115, 0xffff0000, v49
	v_pk_add_f32 v[106:107], v[106:107], v[114:115]
	s_waitcnt vmcnt(3)
	v_lshlrev_b32_e32 v108, 16, v50
	v_and_b32_e32 v109, 0xffff0000, v50
	v_pk_add_f32 v[74:75], v[74:75], v[108:109]
	v_lshlrev_b32_e32 v110, 16, v51
	v_and_b32_e32 v111, 0xffff0000, v51
	v_pk_add_f32 v[76:77], v[76:77], v[110:111]
	v_lshlrev_b32_e32 v112, 16, v52
	v_and_b32_e32 v113, 0xffff0000, v52
	v_pk_add_f32 v[104:105], v[104:105], v[112:113]
	v_lshlrev_b32_e32 v114, 16, v53
	v_and_b32_e32 v115, 0xffff0000, v53
	v_pk_add_f32 v[106:107], v[106:107], v[114:115]
	s_waitcnt vmcnt(2)
	v_lshlrev_b32_e32 v108, 16, v54
	v_and_b32_e32 v109, 0xffff0000, v54
	v_pk_add_f32 v[74:75], v[74:75], v[108:109]
	v_lshlrev_b32_e32 v110, 16, v55
	v_and_b32_e32 v111, 0xffff0000, v55
	v_pk_add_f32 v[76:77], v[76:77], v[110:111]
	v_lshlrev_b32_e32 v112, 16, v56
	v_and_b32_e32 v113, 0xffff0000, v56
	v_pk_add_f32 v[104:105], v[104:105], v[112:113]
	v_lshlrev_b32_e32 v114, 16, v57
	v_and_b32_e32 v115, 0xffff0000, v57
	v_pk_add_f32 v[106:107], v[106:107], v[114:115]
	s_waitcnt vmcnt(1)
	v_lshlrev_b32_e32 v108, 16, v58
	v_and_b32_e32 v109, 0xffff0000, v58
	v_pk_add_f32 v[74:75], v[74:75], v[108:109]
	v_lshlrev_b32_e32 v110, 16, v59
	v_and_b32_e32 v111, 0xffff0000, v59
	v_pk_add_f32 v[76:77], v[76:77], v[110:111]
	v_lshlrev_b32_e32 v112, 16, v60
	v_and_b32_e32 v113, 0xffff0000, v60
	v_pk_add_f32 v[104:105], v[104:105], v[112:113]
	v_lshlrev_b32_e32 v114, 16, v61
	v_and_b32_e32 v115, 0xffff0000, v61
	v_pk_add_f32 v[106:107], v[106:107], v[114:115]
	s_waitcnt vmcnt(0)
	v_lshlrev_b32_e32 v108, 16, v62
	v_and_b32_e32 v109, 0xffff0000, v62
	v_pk_add_f32 v[74:75], v[74:75], v[108:109]
	v_lshlrev_b32_e32 v110, 16, v63
	v_and_b32_e32 v111, 0xffff0000, v63
	v_pk_add_f32 v[76:77], v[76:77], v[110:111]
	v_lshlrev_b32_e32 v112, 16, v64
	v_and_b32_e32 v113, 0xffff0000, v64
	v_pk_add_f32 v[104:105], v[104:105], v[112:113]
	v_lshlrev_b32_e32 v114, 16, v65
	v_and_b32_e32 v115, 0xffff0000, v65
	v_pk_add_f32 v[106:107], v[106:107], v[114:115]
	v_mov_b64_e32 v[70:71], v[104:105]
	v_mov_b64_e32 v[72:73], v[106:107]
